# one static s_setprio 1 for waves 4-7 during the attention phases (reset at phase end), on top of v10
# speedup vs baseline: 1.0043x; 1.0043x over previous
; #define LAS __attribute__((address_space(3)))
; #define ATT_GLOAD(kt) do { _Pragma("unroll") for (int i = 0; i < 3; ++i) kr[i] = *(const u32x4*)(Kbase + (size_t)(kt) * 64 * 192 + kgo + 64 * i); \
;         _Pragma("unroll") for (int i = 0; i < 2; ++i) vr[i] = *(const u32x4*)(Vbase + (size_t)(kt) * 64 * 2048 + vgo + 32 * i * 2048); } while (0)
; #define ATT_LSTORE(st) do { _Pragma("unroll") for (int i = 0; i < 3; ++i) *(LAS u32x4*)(lds + (st) * STG_B + klo + 128 * i) = kr[i]; \
;         _Pragma("unroll") for (int i = 0; i < 2; ++i) *(LAS u32x4*)(lds + (st) * STG_B + vlo + 32 * i * VROW_B) = vr[i]; } while (0)
; DI void attn_block(const bf16_t* Q, const bf16_t* Kb, const bf16_t* Vt, bf16_t* AO, LAS unsigned char* lds, int bh, int qb, int tid, int wave, int lane) {
;     const int b = bh >> 3, h = bh & 7, l31 = lane & 31, hh = lane >> 5;
;     const int q0 = qb * 256, qw = q0 + wave * 32, nkt = 4 * (qb + 1);
;     const bf16_t* Kbase = Kb + (size_t)bh * SEQ * 192; const bf16_t* Vbase = Vt + (size_t)b * SEQ * 2048 + h * 256 + 128;
;     bf16x8 qf[12];
;     { const bf16_t* qp = Q + (size_t)(b * SEQ + qw + l31) * 1536 + h * 192 + 8 * hh;
; #pragma unroll
;       for (int s = 0; s < 12; ++s) qf[s] = *(const bf16x8*)(qp + 16 * s); }
;     f32x16 o[4];
; #pragma unroll
;     for (int d = 0; d < 4; ++d)
; #pragma unroll
;         for (int i = 0; i < 16; ++i) o[d][i] = 0.f;
;     float m = -1e30f, l = 0.f;
;     const int kgo = (tid >> 3) * 192 + (tid & 7) * 8, klo = (tid >> 3) * KROW_B + (tid & 7) * 16;
;     const int vgo = (tid >> 4) * 2048 + (tid & 15) * 8, vlo = KT_B + (tid >> 4) * VROW_B + (tid & 15) * 16;
;     u32x4 kr[3], vr[2];
;     ...
;     ATT_GLOAD(0); ATT_LSTORE(0);
;     __syncthreads();
;     const int koff = l31 * KROW_B + 16 * hh, voff = KT_B + (4 * hh + ((lane >> 2) & 3)) * VROW_B + (16 * ((lane >> 4) & 1) + 4 * (lane & 3)) * 2;
; DI void phase_attn(const bf16_t* Q, const bf16_t* Kb, const bf16_t* Vt, bf16_t* AO, LAS unsigned char* lds, int tid, int wave, int lane, const Grp gr) {
;     for (int k = gr.mi; k < 64; k += gr.GM) {
;         const int pp = gr.grp * 64 + k, bh = pp >> 3, j = pp & 7;
;         attn_block(Q, Kb, Vt, AO, lds, bh, 15 - j, tid, wave, lane);
.LBB0_418:
	s_or_b64 exec, exec, s[0:1]
	s_cmpk_lt_u32 s72, 0x200
	s_cselect_b64 s[2:3], -1, 0
	v_writelane_b32 v253, s2, 32
	s_mov_b64 s[0:1], s[76:77]
	s_mov_b32 s4, s75
	v_mov_b32_e32 v0, 0
	v_mov_b32_e32 v1, 0
	v_writelane_b32 v253, s3, 33
	s_cmpk_gt_u32 s72, 0x1ff
	s_barrier
	s_cbranch_scc1 .LBB0_449
	s_cmp_lt_u32 s75, 4
	s_cbranch_scc1 .Lattn_prio_skip_0
	s_setprio 1
.Lattn_prio_skip_0:
	s_load_dwordx2 s[6:7], s[0:1], 0xf0
	v_readlane_b32 s0, v253, 19
	v_readlane_b32 s2, v253, 27
	v_mbcnt_lo_u32_b32 v1, -1, v1
	v_mbcnt_hi_u32_b32 v1, -1, v1
	s_waitcnt lgkmcnt(0)
	s_add_u32 s8, s6, s0
	s_addc_u32 s9, s7, 0
	s_add_u32 s10, s8, 0x1b080000
	s_addc_u32 s11, s9, 0
	s_add_u32 s0, s8, 0x1c880000
	s_addc_u32 s1, s9, 0
	s_add_u32 s16, s10, s2
	v_readlane_b32 s2, v253, 28
	s_addc_u32 s17, s11, s2
	v_readlane_b32 s2, v253, 24
	s_add_u32 s2, s16, s2
	s_addc_u32 s3, s17, 0
	v_lshl_add_u32 v3, s4, 6, v1
	s_add_u32 s2, s2, 0x4000000
	s_addc_u32 s3, s3, 0
	s_lshl_b32 s19, s4, 5
	v_ashrrev_i32_e32 v7, 3, v3
	s_movk_i32 s4, 0xc0
	v_mul_lo_u32 v2, v7, s4
	v_and_b32_e32 v4, 7, v1
	v_lshl_or_b32 v2, v4, 3, v2
	v_ashrrev_i32_e32 v9, 4, v3
	v_and_b32_e32 v3, 15, v1
	v_lshlrev_b32_e32 v10, 3, v3
	v_lshlrev_b32_e32 v12, 4, v3
	v_ashrrev_i32_e32 v3, 31, v2
	v_lshlrev_b64 v[2:3], 1, v[2:3]
	v_lshlrev_b32_e32 v8, 4, v4
	v_lshl_add_u64 v[4:5], s[10:11], 0, v[2:3]
	s_mov_b64 s[4:5], 0x3400000
	v_lshl_add_u64 v[170:171], v[4:5], 0, s[4:5]
	s_movk_i32 s4, 0x190
	v_ashrrev_i32_e32 v6, 5, v1
	v_mul_lo_u32 v4, v7, s4
	v_and_b32_e32 v196, 31, v1
	v_add3_u32 v197, 0, v4, v8
	v_lshlrev_b32_e32 v4, 4, v6
	v_mad_u32_u24 v199, v196, s4, v4
	v_lshrrev_b32_e32 v4, 2, v1
	v_and_b32_e32 v5, 16, v1
	v_lshlrev_b32_e32 v1, 2, v1
	v_and_or_b32 v1, v1, 12, v5
	v_mbcnt_hi_u32_b32 v5, -1, v252
	v_and_b32_e32 v7, 64, v5
	s_lshr_b32 s18, s72, 3
	v_lshlrev_b32_e32 v168, 3, v6
	v_lshlrev_b32_e32 v174, 2, v6
	v_xor_b32_e32 v6, 32, v5
	v_add_u32_e32 v7, 64, v7
	v_readlane_b32 s4, v253, 23
	s_movk_i32 s12, 0x140
	v_lshl_or_b32 v172, v9, 11, v10
	v_and_or_b32 v4, v4, 3, v174
	v_cmp_lt_i32_e32 vcc, v6, v7
	s_add_u32 s6, s6, s4
	v_ashrrev_i32_e32 v173, 31, v172
	v_mul_lo_u32 v4, v4, s12
	v_cndmask_b32_e32 v5, v5, v6, vcc
	s_addc_u32 s7, s7, 0
	v_lshlrev_b32_e32 v200, 2, v5
	v_lshl_or_b32 v201, v1, 1, v4
	v_lshl_add_u64 v[4:5], v[172:173], 1, s[6:7]
	s_mov_b64 s[6:7], 0x1d4e0100
	v_mul_lo_u32 v11, v9, s12
	v_lshl_add_u64 v[176:177], v[4:5], 0, s[6:7]
	v_lshl_add_u64 v[2:3], s[8:9], 0, v[2:3]
	s_mov_b64 s[6:7], 0x1e486080
	v_ashrrev_i32_e32 v169, 31, v168
	s_mov_b32 s5, 0
	v_add3_u32 v198, 0, v11, v12
	v_ashrrev_i32_e32 v175, 31, v174
	v_lshl_add_u64 v[178:179], v[2:3], 0, s[6:7]
	s_movk_i32 s20, 0xc00
	v_mov_b64_e32 v[180:181], s[0:1]
	v_mov_b32_e32 v202, 0x180000
	s_mov_b64 s[6:7], 0x2400100
	s_mov_b32 s21, 0x2400000
	s_mov_b64 s[8:9], 0x2420100
	s_mov_b32 s22, 0x2420000
	s_mov_b32 s23, 0xf149f2ca
	s_mov_b32 s24, 0x40c00000
	s_mov_b64 s[10:11], 0x40000
	s_mov_b64 s[12:13], 0x6000
	v_mov_b32_e32 v203, 0xf149f2ca
	s_mov_b32 s25, s73
	s_branch .LBB0_422

; #define LAS __attribute__((address_space(3)))
; DI float blo(unsigned u) { return __uint_as_float(u << 16); }
; DI float bhi(unsigned u) { return __uint_as_float(u & 0xffff0000u); }
; DI float gelu_tanh(float x) { const float u = x * (1.f + 0.044715f * x * x); return x * __builtin_amdgcn_rcpf(1.f + __builtin_amdgcn_exp2f(-2.3022081981f * u)); }
; #define GM_LDV(g_) do { _Pragma("unroll") for (int c = 0; c < 4; ++c) va[c] = *(const u32x4*)(zv + (g_) * 128 + 8 * c); } while (0)
; #define GM_LDU(g_) do { bsv = bs[(g_) * 128 + t]; _Pragma("unroll") for (int db = 0; db < 2; ++db) _Pragma("unroll") for (int g4 = 0; g4 < 4; ++g4) uv[db][g4] = *(const u32x2*)(ur + (g_) * 128 + db * 32 + 8 * g4); } while (0)
; DI void phase_gmlp(const bf16_t* Z, const float* gv, const float* Ws, const float* bs, bf16_t* GO, LAS unsigned char* lds, int tid, int wave, int lane, const Grp gr) {
;     LAS bf16_t* vct = (LAS bf16_t*)lds;
;     LAS float* rs = (LAS float*)(lds + 128 * 272);
;     const int l31 = lane & 31, hh = lane >> 5, tb = wave >> 1, dh = wave & 1, nks = 2 * (tb + 1);
;     for (int it = gr.mi; it < 32; it += gr.GM) {
;         const int t0 = (gr.grp * 32 + it) * 128;
;         __syncthreads();
; #pragma unroll
;         for (int rb = 0; rb < 2; ++rb) { u32x4 vv[8][2];
; #pragma unroll
;             for (int r = 0; r < 8; ++r) { const bf16_t* zr = Z + (size_t)(t0 + wave * 16 + rb * 8 + r) * NINP + ZC_V;
; #pragma unroll
;                 for (int j = 0; j < 2; ++j) vv[r][j] = *(const u32x4*)(zr + (lane + 64 * j) * 8); }
; #pragma unroll
;             for (int r = 0; r < 8; ++r) { float s = 0.f;
; #pragma unroll
;                 for (int j = 0; j < 2; ++j)
; #pragma unroll
;                     for (int k = 0; k < 4; ++k) { const float x = gelu_tanh(blo(vv[r][j][k])), y = gelu_tanh(bhi(vv[r][j][k])); s += x * x + y * y; }
;                 s = wave_sum(s); if (lane == 0) rs[wave * 16 + rb * 8 + r] = rsqrtf(s * (1.f / 1024.f) + EPS); } }
;         __syncthreads();
;         const int vs_ = tid >> 2, vdq = tid & 3, t = tb * 32 + l31;
;         const bf16_t* zv = Z + (size_t)(t0 + vs_) * NINP + ZC_V + vdq * 32;
;         const float* wrow = Ws + (size_t)t * 128 + 8 * hh;
;         const bf16_t* ur = Z + (size_t)(t0 + t) * NINP + ZC_U + dh * 64 + 4 * hh;
;         u32x4 va[4]; f32x4 wa[8][2]; u32x2 uv[2][4]; float bsv;
;     ...
;         GM_LDV(0); GM_LDW(0); GM_LDU(0);
.LBB0_449:
	s_setprio 0
	s_cmpk_lt_u32 s72, 0x100
	s_cselect_b64 s[2:3], -1, 0
	v_writelane_b32 v253, s2, 34
	s_mov_b64 s[0:1], s[76:77]
	s_mov_b32 s33, s75
	v_writelane_b32 v253, s3, 35
	v_writelane_b32 v253, s76, 36
	s_cmpk_gt_u32 s72, 0xff
	s_nop 0
	v_writelane_b32 v253, s77, 37
	v_writelane_b32 v253, s75, 38
	v_writelane_b32 v253, s78, 39
	v_writelane_b32 v253, s79, 40
	v_writelane_b32 v253, s80, 41
	v_writelane_b32 v253, s72, 42
	s_cbranch_scc1 .LBB0_572
	s_load_dwordx4 s[56:59], s[0:1], 0xe8
	v_mbcnt_lo_u32_b32 v0, -1, v0
	s_load_dwordx4 s[52:55], s[0:1], 0x78
	s_nop 0
	s_load_dwordx2 s[0:1], s[0:1], 0x88
	v_mbcnt_hi_u32_b32 v14, -1, v0
	v_cmp_eq_u32_e64 s[6:7], 0, v14
	s_waitcnt lgkmcnt(0)
	s_add_u32 s60, s58, s81
	s_addc_u32 s61, s59, 0
	s_add_u32 s70, s60, 0x1b080000
	s_addc_u32 s71, s61, 0
	s_lshl_b32 s3, s33, 6
	s_and_b32 s2, s33, -2
	s_lshl_b32 s4, s33, 4
	s_add_i32 s2, s2, 2
	v_writelane_b32 v253, s6, 43
	s_and_b32 s62, s4, 0xffffffe0
	s_and_b32 s63, s3, 64
	v_writelane_b32 v253, s7, 44
	v_bfi_b32 v146, 31, v14, s4
	s_cmp_gt_i32 s2, 0
	v_writelane_b32 v253, s4, 45
	v_ashrrev_i32_e32 v147, 31, v146
	s_mov_b32 s66, s73
	s_cselect_b64 s[72:73], -1, 0
	s_cmp_lt_u32 s33, 0x7ffffffe
	v_writelane_b32 v253, s3, 47
	v_lshl_add_u64 v[150:151], v[146:147], 2, s[0:1]
	s_cselect_b64 s[0:1], -1, 0
	v_writelane_b32 v253, s0, 49
	s_cmp_gt_i32 s2, 2
	v_ashrrev_i32_e32 v13, 5, v14
	v_writelane_b32 v253, s1, 50
	s_cselect_b64 s[0:1], -1, 0
	v_writelane_b32 v253, s0, 51
	s_cmp_gt_i32 s2, 3
	v_lshlrev_b32_e32 v16, 3, v13
	v_writelane_b32 v253, s1, 52
	s_cselect_b64 s[0:1], -1, 0
	v_writelane_b32 v253, s0, 53
	s_cmp_gt_i32 s2, 4
	v_or_b32_e32 v19, 4, v16
	v_writelane_b32 v253, s1, 54
	s_cselect_b64 s[0:1], -1, 0
	v_writelane_b32 v253, s0, 55
	s_cmp_gt_i32 s2, 5
	v_mbcnt_hi_u32_b32 v0, -1, v252
	v_writelane_b32 v253, s1, 56
	s_cselect_b64 s[0:1], -1, 0
	v_writelane_b32 v253, s0, 57
	s_cmp_gt_i32 s2, 6
	v_and_b32_e32 v1, 64, v0
	v_writelane_b32 v253, s1, 58
	s_cselect_b64 s[0:1], -1, 0
	v_writelane_b32 v253, s0, 59
	s_cmp_gt_i32 s2, 7
	v_add_u32_e32 v1, 64, v1
	v_writelane_b32 v253, s1, 60
	s_cselect_b64 s[0:1], -1, 0
	v_writelane_b32 v253, s0, 61
	v_xor_b32_e32 v4, 1, v0
	v_cmp_lt_i32_e32 vcc, v4, v1
	v_writelane_b32 v253, s1, 62
	v_cmp_gt_i32_e64 s[0:1], v19, v146
	v_or_b32_e32 v19, 5, v16
	v_cmp_gt_i32_e64 s[10:11], v19, v146
	v_or_b32_e32 v19, 2, v16
	v_cmp_gt_i32_e64 s[12:13], v19, v146
	v_or_b32_e32 v19, 6, v16
	v_cmp_gt_i32_e64 s[14:15], v19, v146
	v_or_b32_e32 v19, 3, v16
	v_cmp_gt_i32_e64 s[16:17], v19, v146
	v_or_b32_e32 v19, 7, v16
	v_cmp_gt_i32_e64 s[18:19], v19, v146
	v_add_u32_e32 v19, 16, v16
	v_cmp_gt_i32_e64 s[4:5], v19, v146
	v_add_u32_e32 v19, 20, v16
	v_cndmask_b32_e32 v4, v0, v4, vcc
	v_writelane_b32 v253, s4, 63
	v_lshlrev_b32_e32 v175, 2, v4
	v_xor_b32_e32 v4, 2, v0
	v_writelane_b32 v254, s5, 0
	v_cmp_gt_i32_e64 s[4:5], v19, v146
	v_add_u32_e32 v19, 17, v16
	v_cmp_lt_i32_e32 vcc, v4, v1
	v_writelane_b32 v254, s4, 1
	v_and_b32_e32 v15, 31, v14
	v_cndmask_b32_e32 v4, v0, v4, vcc
	v_writelane_b32 v254, s5, 2
	v_cmp_gt_i32_e64 s[4:5], v19, v146
	v_add_u32_e32 v19, 21, v16
	v_lshlrev_b32_e32 v198, 2, v4
	v_writelane_b32 v254, s4, 3
	v_xor_b32_e32 v4, 4, v0
	v_cmp_lt_i32_e32 vcc, v4, v1
	v_writelane_b32 v254, s5, 4
	v_cmp_gt_i32_e64 s[4:5], v19, v146
	v_add_u32_e32 v19, 18, v16
	v_cndmask_b32_e32 v4, v0, v4, vcc
	v_writelane_b32 v254, s4, 5
	v_lshlrev_b32_e32 v199, 2, v4
	v_xor_b32_e32 v4, 8, v0
	v_writelane_b32 v254, s5, 6
	v_cmp_gt_i32_e64 s[4:5], v19, v146
	v_add_u32_e32 v19, 22, v16
	v_cmp_lt_i32_e32 vcc, v4, v1
	v_writelane_b32 v254, s4, 7
	v_ashrrev_i32_e32 v17, 31, v16
	v_cndmask_b32_e32 v4, v0, v4, vcc
	v_writelane_b32 v254, s5, 8
	v_cmp_gt_i32_e64 s[4:5], v19, v146
	v_add_u32_e32 v19, 19, v16
	v_lshlrev_b32_e32 v200, 2, v4
	v_writelane_b32 v254, s4, 9
	v_xor_b32_e32 v4, 16, v0
	v_cmp_lt_i32_e32 vcc, v4, v1
	v_writelane_b32 v254, s5, 10
	v_cmp_gt_i32_e64 s[4:5], v19, v146
	v_add_u32_e32 v19, 23, v16
	v_cndmask_b32_e32 v4, v0, v4, vcc
	v_writelane_b32 v254, s4, 11
	v_lshlrev_b32_e32 v201, 2, v4
	v_xor_b32_e32 v4, 32, v0
	v_writelane_b32 v254, s5, 12
	v_cmp_gt_i32_e64 s[4:5], v19, v146
	v_add_u32_e32 v19, 32, v16
	v_cmp_lt_i32_e32 vcc, v4, v1
	v_writelane_b32 v254, s4, 13
	v_lshlrev_b64 v[8:9], 2, v[16:17]
	v_or_b32_e32 v17, s63, v15
	v_writelane_b32 v254, s5, 14
	v_cmp_gt_i32_e64 s[4:5], v19, v146
	v_add_u32_e32 v19, 36, v16
	s_lshl_b32 s63, s63, 1
	v_writelane_b32 v254, s4, 15
	v_cndmask_b32_e32 v0, v0, v4, vcc
	s_add_u32 s64, s70, s63
	v_writelane_b32 v254, s5, 16
	v_cmp_gt_i32_e64 s[4:5], v19, v146
	v_add_u32_e32 v19, 33, v16
	v_lshlrev_b32_e32 v202, 2, v0
	v_writelane_b32 v254, s4, 17
	v_lshlrev_b32_e32 v0, 5, v14
	v_lshlrev_b64 v[6:7], 9, v[146:147]
	v_writelane_b32 v254, s5, 18
	v_cmp_gt_i32_e64 s[4:5], v19, v146
	v_add_u32_e32 v19, 37, v16
	s_addc_u32 s65, s71, 0
	v_writelane_b32 v254, s4, 19
	s_and_b32 s33, s33, 1
	v_and_b32_e32 v18, 0x60, v0
	v_writelane_b32 v254, s5, 20
	v_cmp_gt_i32_e64 s[4:5], v19, v146
	v_add_u32_e32 v19, 34, v16
	v_lshl_add_u64 v[0:1], s[54:55], 0, v[6:7]
	v_writelane_b32 v254, s4, 21
	v_lshl_add_u64 v[6:7], v[6:7], 0, v[8:9]
	s_lshl_b32 s63, s33, 7
	v_writelane_b32 v254, s5, 22
	v_cmp_gt_i32_e64 s[4:5], v19, v146
	v_add_u32_e32 v19, 38, v16
	v_lshl_add_u64 v[158:159], s[54:55], 0, v[6:7]
	v_writelane_b32 v254, s4, 23
	s_mov_b64 s[54:55], 0x200
	s_add_u32 s33, s81, s63
	v_writelane_b32 v254, s5, 24
	v_cmp_gt_i32_e64 s[4:5], v19, v146
	v_add_u32_e32 v19, 35, v16
	v_lshlrev_b32_e32 v10, 2, v13
	v_writelane_b32 v254, s4, 25
	v_lshl_add_u64 v[160:161], v[150:151], 0, s[54:55]
	s_addc_u32 s55, 0, 0
; #define GM_LDV(g_) do { _Pragma("unroll") for (int c = 0; c < 4; ++c) va[c] = *(const u32x4*)(zv + (g_) * 128 + 8 * c); } while (0)
; #define GM_LDW(g_) do { _Pragma("unroll") for (int ks = 0; ks < 8; ++ks) if (ks < nks) { wa[ks][0] = *(const f32x4*)(wrow + (size_t)(g_) * 16384 + 16 * ks); wa[ks][1] = *(const f32x4*)(wrow + (size_t)(g_) * 16384 + 16 * ks + 4); } } while (0)
; #define GM_LDU(g_) do { bsv = bs[(g_) * 128 + t]; _Pragma("unroll") for (int db = 0; db < 2; ++db) _Pragma("unroll") for (int g4 = 0; g4 < 4; ++g4) uv[db][g4] = *(const u32x2*)(ur + (g_) * 128 + db * 32 + 8 * g4); } while (0)
; DI void phase_gmlp(const bf16_t* Z, const float* gv, const float* Ws, const float* bs, bf16_t* GO, LAS unsigned char* lds, int tid, int wave, int lane, const Grp gr) {
;     ...
;         const int vs_ = tid >> 2, vdq = tid & 3, t = tb * 32 + l31;
;         const bf16_t* zv = Z + (size_t)(t0 + vs_) * NINP + ZC_V + vdq * 32;
;         const float* wrow = Ws + (size_t)t * 128 + 8 * hh;
;         const bf16_t* ur = Z + (size_t)(t0 + t) * NINP + ZC_U + dh * 64 + 4 * hh;
;         u32x4 va[4]; f32x4 wa[8][2]; u32x2 uv[2][4]; float bsv;
;     ...
;         GM_LDV(0); GM_LDW(0); GM_LDU(0);
	v_writelane_b32 v254, s5, 26
	v_cmp_gt_i32_e64 s[4:5], v19, v146
	v_add_u32_e32 v19, 39, v16
	v_ashrrev_i32_e32 v11, 31, v10
	v_writelane_b32 v254, s4, 27
	s_add_u32 s54, s58, s33
	v_lshlrev_b64 v[10:11], 1, v[10:11]
	v_writelane_b32 v254, s5, 28
	v_cmp_gt_i32_e64 s[4:5], v19, v146
	v_add_u32_e32 v19, 48, v16
	s_addc_u32 s55, s59, s55
	v_writelane_b32 v254, s4, 29
	v_lshl_add_u64 v[6:7], s[54:55], 0, v[10:11]
	s_mov_b64 s[54:55], 0x1b0807c0
	v_writelane_b32 v254, s5, 30
	v_cmp_gt_i32_e64 s[4:5], v19, v146
	v_add_u32_e32 v19, 52, v16
	v_lshl_add_u64 v[162:163], v[6:7], 0, s[54:55]
	v_writelane_b32 v254, s4, 31
	s_lshl_b32 s33, s66, 7
	v_readlane_b32 s54, v253, 1
	v_writelane_b32 v254, s5, 32
	v_cmp_gt_i32_e64 s[4:5], v19, v146
	v_add_u32_e32 v19, 49, v16
	v_add_u32_e32 v3, s3, v14
	v_writelane_b32 v254, s4, 33
	s_add_i32 s33, s54, s33
	v_lshl_add_u64 v[148:149], v[0:1], 0, v[8:9]
	v_writelane_b32 v254, s5, 34
	v_cmp_gt_i32_e64 s[4:5], v19, v146
	v_add_u32_e32 v19, 53, v16
	v_and_b32_e32 v0, -4, v3
	v_writelane_b32 v254, s4, 35
	s_add_i32 s54, s33, s62
	v_add_u32_e32 v147, 0, v0
	v_writelane_b32 v254, s5, 36
	v_cmp_gt_i32_e64 s[4:5], v19, v146
	v_add_u32_e32 v19, 50, v16
	v_mov_b32_e32 v0, 0
	v_writelane_b32 v254, s4, 37
	v_add_u32_e32 v164, s54, v15
	s_lshl_b32 s54, s78, 7
	v_writelane_b32 v254, s5, 38
	v_cmp_gt_i32_e64 s[4:5], v19, v146
	v_add_u32_e32 v19, 54, v16
	v_lshlrev_b32_e32 v2, 3, v14
	v_writelane_b32 v254, s4, 39
	v_ashrrev_i32_e32 v203, 2, v3
	v_lshlrev_b32_e32 v4, 2, v18
	v_writelane_b32 v254, s5, 40
	v_cmp_gt_i32_e64 s[4:5], v19, v146
	v_add_u32_e32 v19, 51, v16
	v_mov_b32_e32 v5, v0
	v_writelane_b32 v254, s4, 41
	v_and_b32_e32 v6, 3, v14
	v_lshl_add_u64 v[152:153], s[52:53], 0, v[4:5]
	v_writelane_b32 v254, s5, 42
	v_cmp_gt_i32_e64 s[4:5], v19, v146
	v_add_u32_e32 v19, 55, v16
	v_lshlrev_b32_e32 v1, 1, v203
	v_writelane_b32 v254, s4, 43
	v_add_u32_e32 v4, 0x200, v2
	v_cmp_gt_i32_e64 s[2:3], v16, v146
	v_writelane_b32 v254, s5, 44
	v_cmp_gt_i32_e64 s[4:5], v19, v146
	v_add_u32_e32 v19, 64, v16
	v_cmp_lt_i32_e64 s[8:9], v16, v146
	v_writelane_b32 v254, s4, 45
	v_lshlrev_b32_e32 v6, 6, v6
	v_mov_b32_e32 v7, v0
	v_writelane_b32 v254, s5, 46
	v_cmp_gt_i32_e64 s[4:5], v19, v146
	v_add_u32_e32 v19, 0x44, v16
	v_sub_u32_e32 v12, v147, v1
	v_writelane_b32 v254, s4, 47
	v_lshl_add_u32 v1, v13, 4, 0
	v_ashrrev_i32_e32 v3, 31, v2
	v_writelane_b32 v254, s5, 48
	v_cmp_gt_i32_e64 s[4:5], v19, v146
	v_add_u32_e32 v19, 0x41, v16
	v_ashrrev_i32_e32 v5, 31, v4
	v_writelane_b32 v254, s4, 49
	v_mul_u32_u24_e32 v13, 0x110, v18
	v_lshlrev_b32_e32 v18, 1, v18
	v_writelane_b32 v254, s5, 50
	v_cmp_gt_i32_e64 s[4:5], v19, v146
	v_add_u32_e32 v19, 0x45, v16
	v_lshl_add_u64 v[6:7], s[60:61], 0, v[6:7]
	v_writelane_b32 v254, s4, 51
	v_lshl_add_u64 v[156:157], s[64:65], 0, v[10:11]
	v_add_u32_e32 v204, s33, v203
	v_writelane_b32 v254, s5, 52
	v_cmp_gt_i32_e64 s[4:5], v19, v146
	v_add_u32_e32 v19, 0x42, v16
	v_mov_b32_e32 v205, 0x358637bd
	v_writelane_b32 v254, s4, 53
	v_add_u32_e32 v206, v12, v13
	v_lshlrev_b64 v[170:171], 1, v[2:3]
	v_writelane_b32 v254, s5, 54
	v_cmp_gt_i32_e64 s[4:5], v19, v146
	v_add_u32_e32 v19, 0x46, v16
	v_lshlrev_b64 v[172:173], 1, v[4:5]
	v_writelane_b32 v254, s4, 55
	s_mov_b32 s33, s66
	v_writelane_b32 v255, s69, 0
	v_writelane_b32 v254, s5, 56
	v_cmp_gt_i32_e64 s[4:5], v19, v146
	v_add_u32_e32 v19, 0x43, v16
	v_cmp_gt_i32_e64 s[82:83], v19, v146
	v_add_u32_e32 v19, 0x47, v16
	v_cmp_gt_i32_e64 s[84:85], v19, v146
	v_add_u32_e32 v19, 0x50, v16
	v_cmp_gt_i32_e64 s[86:87], v19, v146
	v_add_u32_e32 v19, 0x54, v16
	v_cmp_gt_i32_e64 s[88:89], v19, v146
	v_add_u32_e32 v19, 0x51, v16
	v_cmp_gt_i32_e64 s[90:91], v19, v146
	v_add_u32_e32 v19, 0x55, v16
	v_cmp_gt_i32_e64 s[92:93], v19, v146
	v_add_u32_e32 v19, 0x52, v16
	v_cmp_gt_i32_e64 s[94:95], v19, v146
	v_add_u32_e32 v19, 0x56, v16
	v_cmp_gt_i32_e64 s[96:97], v19, v146
	v_add_u32_e32 v19, 0x53, v16
	v_writelane_b32 v254, s4, 57
	v_cmp_gt_i32_e64 s[6:7], v19, v146
	v_add_u32_e32 v19, 0x57, v16
	v_writelane_b32 v254, s5, 58
	v_cmp_gt_i32_e64 s[4:5], v19, v146
	v_add_u32_e32 v19, 0x60, v16
	v_cmp_gt_i32_e64 s[20:21], v19, v146
	v_add_u32_e32 v19, 0x64, v16
	v_cmp_gt_i32_e64 s[22:23], v19, v146
	v_add_u32_e32 v19, 0x61, v16
	v_cmp_gt_i32_e64 s[24:25], v19, v146
	v_add_u32_e32 v19, 0x65, v16
	v_cmp_gt_i32_e64 s[26:27], v19, v146
	v_add_u32_e32 v19, 0x62, v16
	v_cmp_gt_i32_e64 s[28:29], v19, v146
	v_add_u32_e32 v19, 0x66, v16
	v_cmp_gt_i32_e64 s[30:31], v19, v146
	v_add_u32_e32 v19, 0x63, v16
	v_cmp_gt_i32_e64 s[34:35], v19, v146
	v_add_u32_e32 v19, 0x67, v16
	v_cmp_gt_i32_e64 s[36:37], v19, v146
	v_add_u32_e32 v19, 0x70, v16
	v_cmp_gt_i32_e64 s[38:39], v19, v146
	v_add_u32_e32 v19, 0x74, v16
	v_cmp_gt_i32_e64 s[40:41], v19, v146
	v_add_u32_e32 v19, 0x71, v16
	v_cmp_gt_i32_e64 s[42:43], v19, v146
	v_add_u32_e32 v19, 0x75, v16
	v_cmp_gt_i32_e64 s[44:45], v19, v146
	v_add_u32_e32 v19, 0x72, v16
	v_writelane_b32 v254, s81, 59
	v_cmp_gt_i32_e64 s[46:47], v19, v146
	v_add_u32_e32 v19, 0x76, v16
	v_writelane_b32 v254, s54, 60
	s_add_u32 s54, s56, s63
	v_cmp_gt_i32_e64 s[48:49], v19, v146
	v_add_u32_e32 v19, 0x73, v16
	v_add_u32_e32 v16, 0x77, v16
	s_addc_u32 s55, s57, 0
	v_cmp_gt_i32_e64 s[50:51], v19, v146
	v_cmp_gt_i32_e64 s[52:53], v16, v146
	v_mul_u32_u24_e32 v16, 0x110, v17
	v_mov_b32_e32 v19, v0
	v_lshl_add_u64 v[166:167], s[54:55], 0, v[10:11]
	s_mov_b64 s[54:55], 0x1b080fa0
	v_writelane_b32 v254, s66, 61
	v_lshl_add_u64 v[154:155], s[70:71], 0, v[18:19]
	v_lshl_add_u64 v[168:169], v[6:7], 0, s[54:55]
	v_add_u32_e32 v207, v1, v16
	v_writelane_b32 v254, s68, 62
	s_branch .LBB0_452

; #define LAS __attribute__((address_space(3)))
; DI void phase_attn(const bf16_t* Q, const bf16_t* Kb, const bf16_t* Vt, bf16_t* AO, LAS unsigned char* lds, int tid, int wave, int lane, const Grp gr) {
;     for (int k = gr.mi; k < 64; k += gr.GM) {
;         const int pp = gr.grp * 64 + k, bh = pp >> 3, j = pp & 7;
;         attn_block(Q, Kb, Vt, AO, lds, bh, 15 - j, tid, wave, lane);
.LBB0_1164:
	s_or_b64 exec, exec, s[0:1]
	v_readlane_b32 s2, v253, 32
	v_readlane_b32 s3, v253, 33
	s_mov_b64 s[0:1], s[76:77]
	s_mov_b32 s4, s75
	v_mov_b32_e32 v0, 0
	v_mov_b32_e32 v1, 0
	s_andn2_b64 vcc, exec, s[2:3]
	s_barrier
	s_cbranch_vccnz .LBB0_1195
	s_cmp_lt_u32 s75, 4
	s_cbranch_scc1 .Lattn_prio_skip_1
	s_setprio 1

; #define LAS __attribute__((address_space(3)))
; DI float blo(unsigned u) { return __uint_as_float(u << 16); }
; DI float bhi(unsigned u) { return __uint_as_float(u & 0xffff0000u); }
; DI float gelu_tanh(float x) { const float u = x * (1.f + 0.044715f * x * x); return x * __builtin_amdgcn_rcpf(1.f + __builtin_amdgcn_exp2f(-2.3022081981f * u)); }
; #define GM_LDV(g_) do { _Pragma("unroll") for (int c = 0; c < 4; ++c) va[c] = *(const u32x4*)(zv + (g_) * 128 + 8 * c); } while (0)
; #define GM_LDU(g_) do { bsv = bs[(g_) * 128 + t]; _Pragma("unroll") for (int db = 0; db < 2; ++db) _Pragma("unroll") for (int g4 = 0; g4 < 4; ++g4) uv[db][g4] = *(const u32x2*)(ur + (g_) * 128 + db * 32 + 8 * g4); } while (0)
; DI void phase_gmlp(const bf16_t* Z, const float* gv, const float* Ws, const float* bs, bf16_t* GO, LAS unsigned char* lds, int tid, int wave, int lane, const Grp gr) {
;     LAS bf16_t* vct = (LAS bf16_t*)lds;
;     LAS float* rs = (LAS float*)(lds + 128 * 272);
;     const int l31 = lane & 31, hh = lane >> 5, tb = wave >> 1, dh = wave & 1, nks = 2 * (tb + 1);
;     for (int it = gr.mi; it < 32; it += gr.GM) {
;         const int t0 = (gr.grp * 32 + it) * 128;
;         __syncthreads();
; #pragma unroll
;         for (int rb = 0; rb < 2; ++rb) { u32x4 vv[8][2];
; #pragma unroll
;             for (int r = 0; r < 8; ++r) { const bf16_t* zr = Z + (size_t)(t0 + wave * 16 + rb * 8 + r) * NINP + ZC_V;
; #pragma unroll
;                 for (int j = 0; j < 2; ++j) vv[r][j] = *(const u32x4*)(zr + (lane + 64 * j) * 8); }
; #pragma unroll
;             for (int r = 0; r < 8; ++r) { float s = 0.f;
; #pragma unroll
;                 for (int j = 0; j < 2; ++j)
; #pragma unroll
;                     for (int k = 0; k < 4; ++k) { const float x = gelu_tanh(blo(vv[r][j][k])), y = gelu_tanh(bhi(vv[r][j][k])); s += x * x + y * y; }
;                 s = wave_sum(s); if (lane == 0) rs[wave * 16 + rb * 8 + r] = rsqrtf(s * (1.f / 1024.f) + EPS); } }
;         __syncthreads();
;         const int vs_ = tid >> 2, vdq = tid & 3, t = tb * 32 + l31;
;         const bf16_t* zv = Z + (size_t)(t0 + vs_) * NINP + ZC_V + vdq * 32;
;         const float* wrow = Ws + (size_t)t * 128 + 8 * hh;
;         const bf16_t* ur = Z + (size_t)(t0 + t) * NINP + ZC_U + dh * 64 + 4 * hh;
;         u32x4 va[4]; f32x4 wa[8][2]; u32x2 uv[2][4]; float bsv;
;     ...
;         GM_LDV(0); GM_LDW(0); GM_LDU(0);
.LBB0_1195:
	s_setprio 0
	v_readlane_b32 s2, v253, 34
	v_readlane_b32 s3, v253, 35
	s_mov_b64 s[0:1], s[76:77]
	s_mov_b32 s68, s75
	s_andn2_b64 vcc, exec, s[2:3]
	s_cbranch_vccnz .LBB0_1318
	v_mbcnt_lo_u32_b32 v0, -1, v0
	v_mbcnt_hi_u32_b32 v18, -1, v0
	v_mbcnt_hi_u32_b32 v0, -1, v252
	v_and_b32_e32 v1, 64, v0
	v_add_u32_e32 v1, 64, v1
	v_xor_b32_e32 v5, 1, v0
	v_cmp_lt_i32_e32 vcc, v5, v1
	s_load_dwordx4 s[60:63], s[0:1], 0xe8
	s_load_dwordx4 s[64:67], s[0:1], 0x78
	s_load_dwordx2 s[2:3], s[0:1], 0x88
	v_cndmask_b32_e32 v5, v0, v5, vcc
	v_lshlrev_b32_e32 v173, 2, v5
	v_xor_b32_e32 v5, 2, v0
	v_cmp_lt_i32_e32 vcc, v5, v1
	s_waitcnt lgkmcnt(0)
	s_add_u32 s58, s62, s81
	s_addc_u32 s59, s63, 0
	v_cndmask_b32_e32 v5, v0, v5, vcc
	v_lshlrev_b32_e32 v200, 2, v5
	v_xor_b32_e32 v5, 4, v0
	v_cmp_lt_i32_e32 vcc, v5, v1
	s_add_u32 s74, s58, 0x1b080000
	s_addc_u32 s75, s59, 0
	v_cndmask_b32_e32 v5, v0, v5, vcc
	v_lshlrev_b32_e32 v201, 2, v5
	v_xor_b32_e32 v5, 8, v0
	v_cmp_lt_i32_e32 vcc, v5, v1
	s_add_u32 s4, s2, 0x1000
	s_addc_u32 s5, s3, 0
	v_cndmask_b32_e32 v5, v0, v5, vcc
	v_lshlrev_b32_e32 v202, 2, v5
	v_xor_b32_e32 v5, 16, v0
	v_cmp_lt_i32_e32 vcc, v5, v1
	s_and_b32 s0, s68, -2
	s_add_i32 s2, s0, 2
	v_cndmask_b32_e32 v5, v0, v5, vcc
	s_lshl_b32 s0, s68, 4
	v_lshlrev_b32_e32 v203, 2, v5
	v_xor_b32_e32 v5, 32, v0
	v_ashrrev_i32_e32 v4, 5, v18
	v_cmp_lt_i32_e32 vcc, v5, v1
	v_bfi_b32 v146, 31, v18, s0
	s_lshl_b32 s33, s68, 6
	v_cndmask_b32_e32 v0, v0, v5, vcc
	v_ashrrev_i32_e32 v147, 31, v146
	v_lshlrev_b32_e32 v12, 3, v4
	v_lshlrev_b32_e32 v204, 2, v0
	s_and_b32 s69, s0, 0xffffffe0
	v_lshlrev_b32_e32 v0, 5, v18
	v_lshlrev_b64 v[6:7], 9, v[146:147]
	v_ashrrev_i32_e32 v13, 31, v12
	s_and_b32 s70, s33, 64
	v_and_b32_e32 v19, 0x60, v0
	v_lshl_add_u64 v[0:1], s[66:67], 0, v[6:7]
	v_lshlrev_b64 v[8:9], 2, v[12:13]
	s_cmp_gt_i32 s2, 0
	v_writelane_b32 v253, s0, 9
	v_lshl_add_u64 v[0:1], v[0:1], 0, v[8:9]
	s_mov_b64 s[0:1], 0x80000
	s_cselect_b64 s[76:77], -1, 0
	s_cmp_lt_u32 s68, 0x7ffffffe
	v_lshl_add_u64 v[148:149], v[0:1], 0, s[0:1]
	s_cselect_b64 s[0:1], -1, 0
	v_writelane_b32 v254, s0, 62
	s_cmp_gt_i32 s2, 2
	v_or_b32_e32 v13, 4, v12
	v_writelane_b32 v254, s1, 63
	s_cselect_b64 s[0:1], -1, 0
	v_writelane_b32 v255, s0, 0
	s_cmp_gt_i32 s2, 3
	v_cmp_gt_i32_e64 s[10:11], v13, v146
	v_writelane_b32 v255, s1, 1
	s_cselect_b64 s[0:1], -1, 0
	v_writelane_b32 v253, s0, 47
	s_cmp_gt_i32 s2, 4
	v_or_b32_e32 v13, 5, v12
	v_writelane_b32 v253, s1, 48
	s_cselect_b64 s[0:1], -1, 0
	v_writelane_b32 v253, s0, 45
	s_cmp_gt_i32 s2, 5
	v_cmp_gt_i32_e64 s[14:15], v13, v146
	v_writelane_b32 v253, s1, 46
	s_cselect_b64 s[0:1], -1, 0
	v_writelane_b32 v253, s0, 43
	s_cmp_gt_i32 s2, 6
	v_or_b32_e32 v13, 2, v12
	v_writelane_b32 v253, s1, 44
	s_cselect_b64 s[0:1], -1, 0
	v_cmp_gt_i32_e64 s[16:17], v13, v146
	v_or_b32_e32 v13, 6, v12
	v_writelane_b32 v253, s0, 49
	s_cmp_gt_i32 s2, 7
	v_cmp_gt_i32_e64 s[18:19], v13, v146
	v_or_b32_e32 v13, 3, v12
	v_writelane_b32 v253, s1, 50
	s_cselect_b64 s[0:1], -1, 0
	v_cmp_gt_i32_e64 s[20:21], v13, v146
	v_or_b32_e32 v13, 7, v12
	v_writelane_b32 v253, s0, 51
	v_cmp_gt_i32_e64 s[22:23], v13, v146
	v_add_u32_e32 v13, 16, v12
	v_writelane_b32 v253, s1, 52
	v_cmp_gt_i32_e64 s[0:1], v13, v146
	v_add_u32_e32 v13, 20, v12
	v_add_u32_e32 v3, s33, v18
	v_writelane_b32 v253, s0, 63
	v_ashrrev_i32_e32 v205, 2, v3
	s_mov_b64 s[84:85], s[4:5]
	v_writelane_b32 v254, s1, 0
	v_cmp_gt_i32_e64 s[0:1], v13, v146
	v_add_u32_e32 v13, 17, v12
	v_lshl_add_u64 v[150:151], v[146:147], 2, s[4:5]
	v_writelane_b32 v254, s0, 1
	v_and_b32_e32 v0, -4, v3
	v_and_b32_e32 v17, 31, v18
	v_writelane_b32 v254, s1, 2
	v_cmp_gt_i32_e64 s[0:1], v13, v146
	v_add_u32_e32 v13, 21, v12
	v_add_u32_e32 v147, 0, v0
	v_writelane_b32 v254, s0, 3
	v_lshlrev_b32_e32 v0, 1, v205
	v_sub_u32_e32 v14, v147, v0
	v_writelane_b32 v254, s1, 4
	v_cmp_gt_i32_e64 s[0:1], v13, v146
	v_add_u32_e32 v13, 18, v12
	v_or_b32_e32 v0, s70, v17
	v_writelane_b32 v254, s0, 5
	v_mul_u32_u24_e32 v16, 0x110, v0
	v_mov_b32_e32 v0, 0
	v_writelane_b32 v254, s1, 6
	v_cmp_gt_i32_e64 s[0:1], v13, v146
	v_add_u32_e32 v13, 22, v12
	v_lshl_add_u64 v[6:7], v[6:7], 0, v[8:9]
	v_writelane_b32 v254, s0, 7
	v_and_b32_e32 v8, 3, v18
	s_lshl_b32 s70, s70, 1
	v_writelane_b32 v254, s1, 8
	v_cmp_gt_i32_e64 s[0:1], v13, v146
	v_add_u32_e32 v13, 19, v12
	v_lshl_add_u64 v[156:157], s[66:67], 0, v[6:7]
	v_writelane_b32 v254, s0, 9
	v_lshlrev_b32_e32 v6, 7, v8
	v_mov_b32_e32 v7, v0
	v_writelane_b32 v254, s1, 10
	v_cmp_gt_i32_e64 s[0:1], v13, v146
	v_add_u32_e32 v13, 23, v12
	s_add_u32 s70, s74, s70
	v_writelane_b32 v254, s0, 11
	v_lshl_add_u64 v[6:7], s[64:65], 0, v[6:7]
	s_mov_b64 s[64:65], 0x1070
	v_writelane_b32 v254, s1, 12
	v_cmp_gt_i32_e64 s[0:1], v13, v146
	v_add_u32_e32 v13, 32, v12
	s_addc_u32 s71, s75, 0
	v_writelane_b32 v254, s0, 13
	v_lshl_add_u64 v[158:159], v[6:7], 0, s[64:65]
	s_and_b32 s64, s68, 1
	v_writelane_b32 v254, s1, 14
	v_cmp_gt_i32_e64 s[0:1], v13, v146
	v_add_u32_e32 v13, 36, v12
	s_lshl_b32 s64, s64, 7
	v_writelane_b32 v254, s0, 15
	s_add_u32 s65, s81, s64
	v_lshlrev_b32_e32 v10, 2, v4
	v_writelane_b32 v254, s1, 16
	v_cmp_gt_i32_e64 s[0:1], v13, v146
	v_add_u32_e32 v13, 33, v12
	s_addc_u32 s66, 0, 0
	v_writelane_b32 v254, s0, 17
	v_ashrrev_i32_e32 v11, 31, v10
	s_add_u32 s62, s62, s65
	v_writelane_b32 v254, s1, 18
	v_cmp_gt_i32_e64 s[0:1], v13, v146
	v_add_u32_e32 v13, 37, v12
	v_lshlrev_b64 v[10:11], 1, v[10:11]
	v_writelane_b32 v254, s0, 19
	s_addc_u32 s63, s63, s66
	v_lshl_add_u64 v[6:7], s[62:63], 0, v[10:11]
; #define GM_LDV(g_) do { _Pragma("unroll") for (int c = 0; c < 4; ++c) va[c] = *(const u32x4*)(zv + (g_) * 128 + 8 * c); } while (0)
; #define GM_LDW(g_) do { _Pragma("unroll") for (int ks = 0; ks < 8; ++ks) if (ks < nks) { wa[ks][0] = *(const f32x4*)(wrow + (size_t)(g_) * 16384 + 16 * ks); wa[ks][1] = *(const f32x4*)(wrow + (size_t)(g_) * 16384 + 16 * ks + 4); } } while (0)
; #define GM_LDU(g_) do { bsv = bs[(g_) * 128 + t]; _Pragma("unroll") for (int db = 0; db < 2; ++db) _Pragma("unroll") for (int g4 = 0; g4 < 4; ++g4) uv[db][g4] = *(const u32x2*)(ur + (g_) * 128 + db * 32 + 8 * g4); } while (0)
; DI void phase_gmlp(const bf16_t* Z, const float* gv, const float* Ws, const float* bs, bf16_t* GO, LAS unsigned char* lds, int tid, int wave, int lane, const Grp gr) {
;     ...
;         const int vs_ = tid >> 2, vdq = tid & 3, t = tb * 32 + l31;
;         const bf16_t* zv = Z + (size_t)(t0 + vs_) * NINP + ZC_V + vdq * 32;
;         const float* wrow = Ws + (size_t)t * 128 + 8 * hh;
;         const bf16_t* ur = Z + (size_t)(t0 + t) * NINP + ZC_U + dh * 64 + 4 * hh;
;         u32x4 va[4]; f32x4 wa[8][2]; u32x2 uv[2][4]; float bsv;
;     ...
;         GM_LDV(0); GM_LDW(0); GM_LDU(0);
	v_writelane_b32 v254, s1, 20
	v_cmp_gt_i32_e64 s[0:1], v13, v146
	v_add_u32_e32 v13, 34, v12
	s_mov_b64 s[62:63], 0x1b0807c0
	v_writelane_b32 v254, s0, 21
	v_lshl_add_u64 v[160:161], v[6:7], 0, s[62:63]
	s_lshl_b32 s62, s73, 7
	v_writelane_b32 v254, s1, 22
	v_cmp_gt_i32_e64 s[0:1], v13, v146
	v_add_u32_e32 v13, 38, v12
	v_readlane_b32 s63, v253, 1
	v_writelane_b32 v254, s0, 23
	s_add_i32 s62, s63, s62
	s_add_i32 s63, s62, s69
	v_writelane_b32 v254, s1, 24
	v_cmp_gt_i32_e64 s[0:1], v13, v146
	v_add_u32_e32 v13, 35, v12
	v_lshlrev_b32_e32 v6, 6, v8
	v_writelane_b32 v254, s0, 25
	v_mov_b32_e32 v7, v0
	v_lshlrev_b32_e32 v2, 3, v18
	v_writelane_b32 v254, s1, 26
	v_cmp_gt_i32_e64 s[0:1], v13, v146
	v_add_u32_e32 v13, 39, v12
	v_add_u32_e32 v162, s63, v17
	v_writelane_b32 v254, s0, 27
	s_lshl_b32 s63, s78, 7
	v_lshl_add_u64 v[6:7], s[58:59], 0, v[6:7]
	v_writelane_b32 v254, s1, 28
	v_cmp_gt_i32_e64 s[0:1], v13, v146
	v_add_u32_e32 v13, 48, v12
	s_mov_b64 s[58:59], 0x1b080fa0
	v_writelane_b32 v254, s0, 29
	v_cmp_eq_u32_e64 s[82:83], 0, v18
	v_lshl_add_u32 v1, v4, 4, 0
	v_writelane_b32 v254, s1, 30
	v_cmp_gt_i32_e64 s[0:1], v13, v146
	v_add_u32_e32 v13, 52, v12
	v_add_u32_e32 v4, 0x200, v2
	v_writelane_b32 v254, s0, 31
	v_cmp_gt_i32_e64 s[8:9], v12, v146
	v_cmp_lt_i32_e64 s[12:13], v12, v146
	v_writelane_b32 v254, s1, 32
	v_cmp_gt_i32_e64 s[0:1], v13, v146
	v_add_u32_e32 v13, 49, v12
	v_writelane_b32 v253, s63, 53
	v_writelane_b32 v254, s0, 33
	v_lshl_add_u64 v[164:165], v[6:7], 0, s[58:59]
	s_add_u32 s58, s60, s64
	v_writelane_b32 v254, s1, 34
	v_cmp_gt_i32_e64 s[0:1], v13, v146
	v_add_u32_e32 v13, 53, v12
	v_ashrrev_i32_e32 v3, 31, v2
	v_writelane_b32 v254, s0, 35
	v_ashrrev_i32_e32 v5, 31, v4
	v_mul_u32_u24_e32 v15, 0x110, v19
	v_writelane_b32 v254, s1, 36
	v_cmp_gt_i32_e64 s[0:1], v13, v146
	v_add_u32_e32 v13, 50, v12
	s_addc_u32 s59, s61, 0
	v_writelane_b32 v254, s0, 37
	v_writelane_b32 v253, s82, 15
	v_lshl_add_u64 v[154:155], s[70:71], 0, v[10:11]
	v_writelane_b32 v254, s1, 38
	v_cmp_gt_i32_e64 s[0:1], v13, v146
	v_add_u32_e32 v13, 54, v12
	v_add_u32_e32 v206, 0x80, v146
	v_writelane_b32 v254, s0, 39
	v_add_u32_e32 v207, s62, v205
	v_lshl_add_u64 v[166:167], s[58:59], 0, v[10:11]
	v_writelane_b32 v254, s1, 40
	v_cmp_gt_i32_e64 s[0:1], v13, v146
	v_add_u32_e32 v13, 51, v12
	v_mov_b32_e32 v208, 0x358637bd
	v_writelane_b32 v254, s0, 41
	v_add_u32_e32 v209, v14, v15
	v_lshlrev_b64 v[168:169], 1, v[2:3]
	v_writelane_b32 v254, s1, 42
	v_cmp_gt_i32_e64 s[0:1], v13, v146
	v_add_u32_e32 v13, 55, v12
	v_lshlrev_b64 v[170:171], 1, v[4:5]
	v_writelane_b32 v254, s0, 43
	v_add_u32_e32 v210, v1, v16
	v_writelane_b32 v253, s83, 16
	v_writelane_b32 v254, s1, 44
	v_cmp_gt_i32_e64 s[0:1], v13, v146
	v_add_u32_e32 v13, 64, v12
	s_nop 0
	v_writelane_b32 v254, s0, 45
	s_nop 1
	v_writelane_b32 v254, s1, 46
	v_cmp_gt_i32_e64 s[0:1], v13, v146
	v_add_u32_e32 v13, 0x44, v12
	s_nop 0
	v_writelane_b32 v254, s0, 47
	s_nop 1
	v_writelane_b32 v254, s1, 48
	v_cmp_gt_i32_e64 s[0:1], v13, v146
	v_add_u32_e32 v13, 0x41, v12
	s_nop 0
	v_writelane_b32 v254, s0, 49
	s_nop 1
	v_writelane_b32 v254, s1, 50
	v_cmp_gt_i32_e64 s[0:1], v13, v146
	v_add_u32_e32 v13, 0x45, v12
	s_nop 0
	v_writelane_b32 v254, s0, 51
	s_nop 1
	v_writelane_b32 v254, s1, 52
	v_cmp_gt_i32_e64 s[0:1], v13, v146
	v_add_u32_e32 v13, 0x42, v12
	s_nop 0
	v_writelane_b32 v254, s0, 53
	s_nop 1
	v_writelane_b32 v254, s1, 54
	v_cmp_gt_i32_e64 s[0:1], v13, v146
	v_add_u32_e32 v13, 0x46, v12
	s_nop 0
	v_writelane_b32 v254, s0, 55
	s_nop 1
	v_writelane_b32 v254, s1, 56
	v_cmp_gt_i32_e64 s[0:1], v13, v146
	v_add_u32_e32 v13, 0x43, v12
	v_cmp_gt_i32_e64 s[86:87], v13, v146
	v_add_u32_e32 v13, 0x47, v12
	v_cmp_gt_i32_e64 s[88:89], v13, v146
	v_add_u32_e32 v13, 0x50, v12
	v_cmp_gt_i32_e64 s[90:91], v13, v146
	v_add_u32_e32 v13, 0x54, v12
	v_cmp_gt_i32_e64 s[92:93], v13, v146
	v_add_u32_e32 v13, 0x51, v12
	v_cmp_gt_i32_e64 s[94:95], v13, v146
	v_add_u32_e32 v13, 0x55, v12
	v_cmp_gt_i32_e64 s[96:97], v13, v146
	v_add_u32_e32 v13, 0x52, v12
	v_cmp_gt_i32_e64 s[4:5], v13, v146
	v_add_u32_e32 v13, 0x56, v12
	v_cmp_gt_i32_e64 s[2:3], v13, v146
	v_add_u32_e32 v13, 0x53, v12
	v_writelane_b32 v254, s0, 57
	v_cmp_gt_i32_e64 s[6:7], v13, v146
	v_add_u32_e32 v13, 0x57, v12
	v_writelane_b32 v254, s1, 58
	v_cmp_gt_i32_e64 s[0:1], v13, v146
	v_add_u32_e32 v13, 0x60, v12
	v_cmp_gt_i32_e64 s[24:25], v13, v146
	v_add_u32_e32 v13, 0x64, v12
	v_cmp_gt_i32_e64 s[26:27], v13, v146
	v_add_u32_e32 v13, 0x61, v12
	v_cmp_gt_i32_e64 s[28:29], v13, v146
	v_add_u32_e32 v13, 0x65, v12
	v_cmp_gt_i32_e64 s[30:31], v13, v146
	v_add_u32_e32 v13, 0x62, v12
	v_cmp_gt_i32_e64 s[34:35], v13, v146
	v_add_u32_e32 v13, 0x66, v12
	v_cmp_gt_i32_e64 s[36:37], v13, v146
	v_add_u32_e32 v13, 0x63, v12
	v_cmp_gt_i32_e64 s[38:39], v13, v146
	v_add_u32_e32 v13, 0x67, v12
	v_cmp_gt_i32_e64 s[40:41], v13, v146
	v_add_u32_e32 v13, 0x70, v12
	v_cmp_gt_i32_e64 s[42:43], v13, v146
	v_add_u32_e32 v13, 0x74, v12
	v_cmp_gt_i32_e64 s[44:45], v13, v146
	v_add_u32_e32 v13, 0x71, v12
	v_cmp_gt_i32_e64 s[46:47], v13, v146
	v_add_u32_e32 v13, 0x75, v12
	v_cmp_gt_i32_e64 s[48:49], v13, v146
	v_add_u32_e32 v13, 0x72, v12
	v_cmp_gt_i32_e64 s[50:51], v13, v146
	v_add_u32_e32 v13, 0x76, v12
	v_cmp_gt_i32_e64 s[52:53], v13, v146
	v_add_u32_e32 v13, 0x73, v12
	v_add_u32_e32 v12, 0x77, v12
	v_cmp_gt_i32_e64 s[54:55], v13, v146
	v_cmp_gt_i32_e64 s[56:57], v12, v146
	v_lshlrev_b32_e32 v12, 1, v19
	v_mov_b32_e32 v13, v0
	v_lshl_add_u64 v[152:153], s[74:75], 0, v[12:13]
	s_branch .LBB0_1198
